# defer 17920 w_down conversion items (16 per wave) into P1 tail
# baseline (speedup 1.0000x reference)
.LBB0_9:
	s_cmp_lg_u32 s101, 0
	s_cbranch_scc1 .Lcv_go
	s_cmp_lt_i32 s80, 0x16480
	s_cbranch_scc1 .Lcv_go
	s_cmp_lt_i32 s80, 0x1aa80
	s_cbranch_scc1 .LBB0_8

.LBB0_415:
	s_waitcnt vmcnt(0)
	s_barrier
	v_writelane_b32 v248, s0, 0
	v_writelane_b32 v248, s1, 1
	v_writelane_b32 v248, s2, 2
	v_writelane_b32 v248, s3, 3
	v_writelane_b32 v248, s4, 4
	v_writelane_b32 v248, s5, 5
	v_writelane_b32 v248, s6, 6
	v_writelane_b32 v248, s7, 7
	v_writelane_b32 v248, s8, 8
	v_writelane_b32 v248, s9, 9
	v_writelane_b32 v248, s10, 10
	v_writelane_b32 v248, s11, 11
	v_writelane_b32 v248, s12, 12
	v_writelane_b32 v248, s13, 13
	v_writelane_b32 v248, s14, 14
	v_writelane_b32 v248, s15, 15
	v_writelane_b32 v248, s16, 16
	v_writelane_b32 v248, s17, 17
	v_writelane_b32 v248, s18, 18
	v_writelane_b32 v248, s19, 19
	v_writelane_b32 v248, s20, 20
	v_writelane_b32 v248, s21, 21
	v_writelane_b32 v248, s22, 22
	v_writelane_b32 v248, s23, 23
	v_writelane_b32 v248, s24, 24
	v_writelane_b32 v248, s25, 25
	v_writelane_b32 v248, s26, 26
	v_writelane_b32 v248, s27, 27
	v_writelane_b32 v248, s28, 28
	v_writelane_b32 v248, s29, 29
	v_writelane_b32 v248, s30, 30
	v_writelane_b32 v248, s31, 31
	v_writelane_b32 v248, s32, 32
	v_writelane_b32 v248, s33, 33
	v_writelane_b32 v248, s34, 34
	v_writelane_b32 v248, s35, 35
	v_writelane_b32 v248, s36, 36
	v_writelane_b32 v248, s37, 37
	v_writelane_b32 v248, s38, 38
	v_writelane_b32 v248, s39, 39
	v_writelane_b32 v248, s40, 40
	v_writelane_b32 v248, s41, 41
	v_writelane_b32 v248, s42, 42
	v_writelane_b32 v248, s43, 43
	v_writelane_b32 v248, s44, 44
	v_writelane_b32 v248, s45, 45
	v_writelane_b32 v248, s46, 46
	v_writelane_b32 v248, s47, 47
	v_writelane_b32 v248, s48, 48
	v_writelane_b32 v248, s49, 49
	v_writelane_b32 v248, s50, 50
	v_writelane_b32 v248, s51, 51
	v_writelane_b32 v248, s52, 52
	v_writelane_b32 v248, s53, 53
	v_writelane_b32 v248, s54, 54
	v_writelane_b32 v248, s55, 55
	v_writelane_b32 v248, s56, 56
	v_writelane_b32 v248, s57, 57
	v_writelane_b32 v248, s58, 58
	v_writelane_b32 v248, s59, 59
	v_writelane_b32 v248, s60, 60
	v_writelane_b32 v248, s61, 61
	v_writelane_b32 v248, s62, 62
	v_writelane_b32 v248, s63, 63
	v_writelane_b32 v249, s64, 0
	v_writelane_b32 v249, s65, 1
	v_writelane_b32 v249, s66, 2
	v_writelane_b32 v249, s67, 3
	v_writelane_b32 v249, s68, 4
	v_writelane_b32 v249, s69, 5
	v_writelane_b32 v249, s70, 6
	v_writelane_b32 v249, s71, 7
	v_writelane_b32 v249, s72, 8
	v_writelane_b32 v249, s73, 9
	v_writelane_b32 v249, s74, 10
	v_writelane_b32 v249, s75, 11
	v_writelane_b32 v249, s76, 12
	v_writelane_b32 v249, s77, 13
	v_writelane_b32 v249, s78, 14
	v_writelane_b32 v249, s79, 15
	v_writelane_b32 v249, s80, 16
	v_writelane_b32 v249, s81, 17
	v_writelane_b32 v249, s82, 18
	v_writelane_b32 v249, s83, 19
	v_writelane_b32 v249, s84, 20
	v_writelane_b32 v249, s85, 21
	v_writelane_b32 v249, s86, 22
	v_writelane_b32 v249, s87, 23
	v_writelane_b32 v249, s88, 24
	v_writelane_b32 v249, s89, 25
	v_writelane_b32 v249, s90, 26
	v_writelane_b32 v249, s91, 27
	v_writelane_b32 v249, s92, 28
	v_writelane_b32 v249, s93, 29
	v_writelane_b32 v249, s94, 30
	v_writelane_b32 v249, s95, 31
	v_writelane_b32 v249, s96, 32
	v_writelane_b32 v249, s97, 33
	v_readlane_b32 s1, v250, 9
	v_readlane_b32 s86, v250, 10
	v_readlane_b32 s87, v250, 11
	s_sub_i32 s0, s2, 0x74
	s_lshl_b32 s0, s0, 3
	s_nop 1
	s_add_i32 s12, s0, s1
	s_add_i32 s12, s12, 0x16480
	s_movk_i32 s14, 0x460
	s_mov_b32 s100, 0x1aa80
	s_mov_b32 s101, 1
	s_branch .Lcv_entry
